# tnt: streaming (nt) hint on the read-once f32 weight loads of the P0 transposes, on top of v78
# baseline (speedup 1.0000x reference)
; #define LAS __attribute__((address_space(3)))
; template <bool MAPIN>
; __device__ __forceinline__ void transpose_item(const float* W, int K, int N, bf16_t* WT, LAS float* scr, int item, int lane, const float* gk = nullptr) {
;     ...
;     for (int i = 0; i < 32; ++i) { const int kk = 2 * i + (lane >> 5); scr[kk * 33 + (lane & 31)] = W[(size_t)(k0 + kk) * N + n0 + (lane & 31)]; }
;     asm volatile("s_waitcnt lgkmcnt(0)" ::: "memory");
;     const int c = lane & 7;
; #pragma unroll
;     for (int j = 0; j < 4; ++j) { const int n = (lane >> 3) + 8 * j; const LAS float* s = scr + (8 * c) * 33 + n;
;         f32x4 ga = (f32x4){1.f, 1.f, 1.f, 1.f}, gb = ga;
;         if (gk) { ga = *(const f32x4*)(gk + k0 + 8 * c); gb = *(const f32x4*)(gk + k0 + 8 * c + 4); }
.LBB0_108:
	s_lshl_b32 s19, s16, 1
	s_lshl_b32 s20, s17, 1
	v_or_b32_e32 v14, s20, v4
	s_add_i32 s22, s19, 4
	s_add_i32 s23, s20, 4
	v_mov_b32_e32 v9, v15
	s_add_i32 s25, s20, 8
	v_lshlrev_b64 v[48:49], 13, v[14:15]
	v_or_b32_e32 v8, s22, v5
	v_or_b32_e32 v14, s23, v4
	v_mov_b32_e32 v7, v15
	v_or_b32_e32 v6, s19, v5
	s_add_i32 s27, s20, 12
	v_lshlrev_b64 v[8:9], 13, v[8:9]
	v_lshlrev_b64 v[50:51], 13, v[14:15]
	v_or_b32_e32 v14, s25, v4
	s_add_i32 s24, s19, 8
	s_add_i32 s26, s19, 12
	s_add_i32 s29, s20, 16
	v_lshlrev_b64 v[6:7], 13, v[6:7]
	v_lshl_add_u64 v[48:49], v[2:3], 0, v[48:49]
	v_lshl_add_u64 v[8:9], v[2:3], 0, v[8:9]
	v_lshlrev_b64 v[52:53], 13, v[14:15]
	v_or_b32_e32 v14, s27, v4
	v_mov_b32_e32 v23, v15
	v_mov_b32_e32 v39, v15
	s_add_i32 s31, s20, 20
	v_or_b32_e32 v22, s24, v5
	v_or_b32_e32 v38, s26, v5
	v_lshl_add_u64 v[6:7], v[2:3], 0, v[6:7]
	v_lshl_add_u64 v[50:51], v[2:3], 0, v[50:51]
	global_load_dword v21, v[48:49], off nt
	global_load_dword v25, v[6:7], off nt
	global_load_dword v65, v[50:51], off nt
	global_load_dword v67, v[8:9], off nt
	v_lshlrev_b64 v[8:9], 13, v[14:15]
	v_or_b32_e32 v14, s29, v4
	s_add_i32 s28, s19, 16
	s_add_i32 s30, s19, 20
	s_add_i32 s35, s20, 24
	v_lshlrev_b64 v[22:23], 13, v[22:23]
	v_lshlrev_b64 v[38:39], 13, v[38:39]
	v_lshl_add_u64 v[6:7], v[2:3], 0, v[52:53]
	v_lshl_add_u64 v[8:9], v[2:3], 0, v[8:9]
	v_lshlrev_b64 v[48:49], 13, v[14:15]
	v_or_b32_e32 v14, s31, v4
	v_mov_b32_e32 v41, v15
	v_mov_b32_e32 v43, v15
	s_add_i32 s34, s19, 24
	s_add_i32 s76, s19, 28
	s_add_i32 s77, s20, 28
	v_or_b32_e32 v40, s28, v5
	v_or_b32_e32 v42, s30, v5
	v_lshl_add_u64 v[22:23], v[2:3], 0, v[22:23]
	v_lshl_add_u64 v[38:39], v[2:3], 0, v[38:39]
	global_load_dword v68, v[6:7], off nt
	global_load_dword v69, v[22:23], off nt
	global_load_dword v70, v[8:9], off nt
	global_load_dword v71, v[38:39], off nt
	v_lshlrev_b64 v[8:9], 13, v[14:15]
	v_or_b32_e32 v14, s35, v4
	v_mov_b32_e32 v45, v15
	v_mov_b32_e32 v47, v15
	v_or_b32_e32 v44, s34, v5
	v_or_b32_e32 v46, s76, v5
	v_lshlrev_b64 v[40:41], 13, v[40:41]
	v_lshlrev_b64 v[42:43], 13, v[42:43]
	v_lshl_add_u64 v[6:7], v[2:3], 0, v[48:49]
	v_lshl_add_u64 v[8:9], v[2:3], 0, v[8:9]
	v_lshlrev_b64 v[22:23], 13, v[14:15]
	v_or_b32_e32 v14, s77, v4
	v_lshlrev_b64 v[44:45], 13, v[44:45]
	v_lshlrev_b64 v[46:47], 13, v[46:47]
	v_lshl_add_u64 v[40:41], v[2:3], 0, v[40:41]
	v_lshl_add_u64 v[42:43], v[2:3], 0, v[42:43]
	global_load_dword v72, v[6:7], off nt
	global_load_dword v73, v[40:41], off nt
	global_load_dword v74, v[8:9], off nt
	global_load_dword v75, v[42:43], off nt
	v_lshl_add_u64 v[6:7], v[2:3], 0, v[22:23]
	v_lshlrev_b64 v[8:9], 13, v[14:15]
	v_lshl_add_u64 v[44:45], v[2:3], 0, v[44:45]
	v_lshl_add_u64 v[46:47], v[2:3], 0, v[46:47]
	v_lshl_add_u64 v[8:9], v[2:3], 0, v[8:9]
	global_load_dword v14, v[6:7], off nt
	global_load_dword v76, v[44:45], off nt
	global_load_dword v77, v[8:9], off nt
	global_load_dword v78, v[46:47], off nt
	v_or_b32_e32 v8, s19, v13
	v_or_b32_e32 v6, s20, v12
	s_add_i32 s17, s17, 16
	s_add_i32 s16, s16, 16
	s_add_i32 s18, s18, -16
	v_mad_u64_u32 v[6:7], s[20:21], v6, s36, v[16:17]
	v_mad_u64_u32 v[8:9], s[20:21], v8, s36, v[16:17]
	v_or_b32_e32 v7, s22, v13
	v_or_b32_e32 v9, s23, v12
	v_or_b32_e32 v42, s24, v13
	v_or_b32_e32 v40, s25, v12
	v_or_b32_e32 v46, s26, v13
	v_or_b32_e32 v44, s27, v12
	v_or_b32_e32 v50, s28, v13
	v_or_b32_e32 v48, s29, v12
	v_or_b32_e32 v54, s30, v13
	v_or_b32_e32 v52, s31, v12
	v_or_b32_e32 v58, s34, v13
	v_or_b32_e32 v56, s35, v12
	v_or_b32_e32 v62, s76, v13
	v_or_b32_e32 v60, s77, v12
	s_cmp_lg_u32 s18, 0
	v_mad_u64_u32 v[22:23], s[20:21], v9, s36, v[16:17]
	v_mad_u64_u32 v[38:39], s[20:21], v7, s36, v[16:17]
	v_mad_u64_u32 v[40:41], s[20:21], v40, s36, v[16:17]
	v_mad_u64_u32 v[42:43], s[20:21], v42, s36, v[16:17]
	v_mad_u64_u32 v[44:45], s[20:21], v44, s36, v[16:17]
	v_mad_u64_u32 v[46:47], s[20:21], v46, s36, v[16:17]
	v_mad_u64_u32 v[48:49], s[20:21], v48, s36, v[16:17]
	v_mad_u64_u32 v[50:51], s[20:21], v50, s36, v[16:17]
	v_mad_u64_u32 v[52:53], s[20:21], v52, s36, v[16:17]
	v_mad_u64_u32 v[54:55], s[20:21], v54, s36, v[16:17]
	v_mad_u64_u32 v[56:57], s[20:21], v56, s36, v[16:17]
	v_mad_u64_u32 v[58:59], s[20:21], v58, s36, v[16:17]
	v_mad_u64_u32 v[60:61], s[20:21], v60, s36, v[16:17]
	v_mad_u64_u32 v[62:63], s[20:21], v62, s36, v[16:17]
	v_mov_b32_e32 v145, v15
	s_lshl_b32 s19, s16, 1
	s_lshl_b32 s20, s17, 1
	v_or_b32_e32 v144, s20, v4
	s_add_i32 s22, s19, 4
	s_add_i32 s23, s20, 4
	v_mov_b32_e32 v139, v145
	s_add_i32 s25, s20, 8
	v_lshlrev_b64 v[178:179], 13, v[144:145]
	v_or_b32_e32 v138, s22, v5
	v_or_b32_e32 v144, s23, v4
	v_mov_b32_e32 v137, v145
	v_or_b32_e32 v136, s19, v5
	s_add_i32 s27, s20, 12
	v_lshlrev_b64 v[138:139], 13, v[138:139]
	v_lshlrev_b64 v[180:181], 13, v[144:145]
	v_or_b32_e32 v144, s25, v4
	s_add_i32 s24, s19, 8
	s_add_i32 s26, s19, 12
	s_add_i32 s29, s20, 16
	v_lshlrev_b64 v[136:137], 13, v[136:137]
	v_lshl_add_u64 v[178:179], v[2:3], 0, v[178:179]
	v_lshl_add_u64 v[138:139], v[2:3], 0, v[138:139]
	v_lshlrev_b64 v[182:183], 13, v[144:145]
	v_or_b32_e32 v144, s27, v4
	v_mov_b32_e32 v153, v145
	v_mov_b32_e32 v169, v145
	s_add_i32 s31, s20, 20
	v_or_b32_e32 v152, s24, v5
	v_or_b32_e32 v168, s26, v5
	v_lshl_add_u64 v[136:137], v[2:3], 0, v[136:137]
; #define LAS __attribute__((address_space(3)))
; template <bool MAPIN>
; __device__ __forceinline__ void transpose_item(const float* W, int K, int N, bf16_t* WT, LAS float* scr, int item, int lane, const float* gk = nullptr) {
;     ...
;     for (int i = 0; i < 32; ++i) { const int kk = 2 * i + (lane >> 5); scr[kk * 33 + (lane & 31)] = W[(size_t)(k0 + kk) * N + n0 + (lane & 31)]; }
;     asm volatile("s_waitcnt lgkmcnt(0)" ::: "memory");
;     const int c = lane & 7;
; #pragma unroll
;     for (int j = 0; j < 4; ++j) { const int n = (lane >> 3) + 8 * j; const LAS float* s = scr + (8 * c) * 33 + n;
;         f32x4 ga = (f32x4){1.f, 1.f, 1.f, 1.f}, gb = ga;
;         if (gk) { ga = *(const f32x4*)(gk + k0 + 8 * c); gb = *(const f32x4*)(gk + k0 + 8 * c + 4); }
	v_lshl_add_u64 v[180:181], v[2:3], 0, v[180:181]
	global_load_dword v151, v[178:179], off nt
	global_load_dword v155, v[136:137], off nt
	global_load_dword v195, v[180:181], off nt
	global_load_dword v197, v[138:139], off nt
	v_lshlrev_b64 v[138:139], 13, v[144:145]
	v_or_b32_e32 v144, s29, v4
	s_add_i32 s28, s19, 16
	s_add_i32 s30, s19, 20
	s_add_i32 s35, s20, 24
	v_lshlrev_b64 v[152:153], 13, v[152:153]
	v_lshlrev_b64 v[168:169], 13, v[168:169]
	v_lshl_add_u64 v[136:137], v[2:3], 0, v[182:183]
	v_lshl_add_u64 v[138:139], v[2:3], 0, v[138:139]
	v_lshlrev_b64 v[178:179], 13, v[144:145]
	v_or_b32_e32 v144, s31, v4
	v_mov_b32_e32 v171, v145
	v_mov_b32_e32 v173, v145
	s_add_i32 s34, s19, 24
	s_add_i32 s76, s19, 28
	s_add_i32 s77, s20, 28
	v_or_b32_e32 v170, s28, v5
	v_or_b32_e32 v172, s30, v5
	v_lshl_add_u64 v[152:153], v[2:3], 0, v[152:153]
	v_lshl_add_u64 v[168:169], v[2:3], 0, v[168:169]
	global_load_dword v198, v[136:137], off nt
	global_load_dword v199, v[152:153], off nt
	global_load_dword v200, v[138:139], off nt
	global_load_dword v201, v[168:169], off nt
	v_lshlrev_b64 v[138:139], 13, v[144:145]
	v_or_b32_e32 v144, s35, v4
	v_mov_b32_e32 v175, v145
	v_mov_b32_e32 v177, v145
	v_or_b32_e32 v174, s34, v5
	v_or_b32_e32 v176, s76, v5
	v_lshlrev_b64 v[170:171], 13, v[170:171]
	v_lshlrev_b64 v[172:173], 13, v[172:173]
	v_lshl_add_u64 v[136:137], v[2:3], 0, v[178:179]
	v_lshl_add_u64 v[138:139], v[2:3], 0, v[138:139]
	v_lshlrev_b64 v[152:153], 13, v[144:145]
	v_or_b32_e32 v144, s77, v4
	v_lshlrev_b64 v[174:175], 13, v[174:175]
	v_lshlrev_b64 v[176:177], 13, v[176:177]
	v_lshl_add_u64 v[170:171], v[2:3], 0, v[170:171]
	v_lshl_add_u64 v[172:173], v[2:3], 0, v[172:173]
	global_load_dword v202, v[136:137], off nt
	global_load_dword v203, v[170:171], off nt
	global_load_dword v204, v[138:139], off nt
	global_load_dword v205, v[172:173], off nt
	v_lshl_add_u64 v[136:137], v[2:3], 0, v[152:153]
	v_lshlrev_b64 v[138:139], 13, v[144:145]
	v_lshl_add_u64 v[174:175], v[2:3], 0, v[174:175]
	v_lshl_add_u64 v[176:177], v[2:3], 0, v[176:177]
	v_lshl_add_u64 v[138:139], v[2:3], 0, v[138:139]
	global_load_dword v144, v[136:137], off nt
	global_load_dword v206, v[174:175], off nt
	global_load_dword v207, v[138:139], off nt
	global_load_dword v208, v[176:177], off nt
	v_or_b32_e32 v138, s19, v13
	v_or_b32_e32 v136, s20, v12
	s_add_i32 s17, s17, 16
	s_add_i32 s16, s16, 16
	s_add_i32 s18, s18, -16
	v_mad_u64_u32 v[136:137], s[20:21], v136, s36, v[16:17]
	v_mad_u64_u32 v[138:139], s[20:21], v138, s36, v[16:17]
	v_or_b32_e32 v137, s22, v13
	v_or_b32_e32 v139, s23, v12
	v_or_b32_e32 v172, s24, v13
	v_or_b32_e32 v170, s25, v12
	v_or_b32_e32 v176, s26, v13
	v_or_b32_e32 v174, s27, v12
	v_or_b32_e32 v180, s28, v13
	v_or_b32_e32 v178, s29, v12
	v_or_b32_e32 v184, s30, v13
	v_or_b32_e32 v182, s31, v12
	v_or_b32_e32 v188, s34, v13
	v_or_b32_e32 v186, s35, v12
	v_or_b32_e32 v192, s76, v13
	v_or_b32_e32 v190, s77, v12
	s_cmp_lg_u32 s18, 0
	v_mad_u64_u32 v[152:153], s[20:21], v139, s36, v[16:17]
	v_mad_u64_u32 v[168:169], s[20:21], v137, s36, v[16:17]
	v_mad_u64_u32 v[170:171], s[20:21], v170, s36, v[16:17]
	v_mad_u64_u32 v[172:173], s[20:21], v172, s36, v[16:17]
	v_mad_u64_u32 v[174:175], s[20:21], v174, s36, v[16:17]
	v_mad_u64_u32 v[176:177], s[20:21], v176, s36, v[16:17]
	v_mad_u64_u32 v[178:179], s[20:21], v178, s36, v[16:17]
	v_mad_u64_u32 v[180:181], s[20:21], v180, s36, v[16:17]
	v_mad_u64_u32 v[182:183], s[20:21], v182, s36, v[16:17]
	v_mad_u64_u32 v[184:185], s[20:21], v184, s36, v[16:17]
	v_mad_u64_u32 v[186:187], s[20:21], v186, s36, v[16:17]
	v_mad_u64_u32 v[188:189], s[20:21], v188, s36, v[16:17]
	v_mad_u64_u32 v[190:191], s[20:21], v190, s36, v[16:17]
	v_mad_u64_u32 v[192:193], s[20:21], v192, s36, v[16:17]
	s_waitcnt vmcnt(0)
	ds_write_b32 v6, v21
	ds_write_b32 v8, v25
	ds_write_b32 v22, v65
	ds_write_b32 v38, v67
	ds_write_b32 v40, v68
	ds_write_b32 v42, v69
	ds_write_b32 v44, v70
	ds_write_b32 v46, v71
	ds_write_b32 v48, v72
	ds_write_b32 v50, v73
	ds_write_b32 v52, v74
	ds_write_b32 v54, v75
	ds_write_b32 v56, v14
	ds_write_b32 v58, v76
	ds_write_b32 v60, v77
	ds_write_b32 v62, v78
	ds_write_b32 v136, v151
	ds_write_b32 v138, v155
	ds_write_b32 v152, v195
	ds_write_b32 v168, v197
	ds_write_b32 v170, v198
	ds_write_b32 v172, v199
	ds_write_b32 v174, v200
	ds_write_b32 v176, v201
	ds_write_b32 v178, v202
	ds_write_b32 v180, v203
	ds_write_b32 v182, v204
	ds_write_b32 v184, v205
	ds_write_b32 v186, v144
	ds_write_b32 v188, v206
	ds_write_b32 v190, v207
	ds_write_b32 v192, v208
	s_waitcnt lgkmcnt(0)
	v_lshlrev_b32_e32 v14, 2, v24
	v_cmp_ne_u64_e32 vcc, 0, v[0:1]
	v_lshl_add_u64 v[0:1], v[0:1], 0, v[14:15]
	v_lshlrev_b32_e32 v14, 2, v18
	v_lshl_add_u64 v[22:23], v[0:1], 0, v[14:15]
	v_mov_b32_e32 v0, 1.0
	v_mov_b32_e32 v6, 1.0
	v_mov_b32_e32 v7, 1.0
	v_mov_b32_e32 v8, 1.0
	v_mov_b32_e32 v9, 1.0
	v_mov_b32_e32 v2, 1.0
	v_mov_b32_e32 v3, 1.0
	v_mov_b32_e32 v4, 1.0
	v_mov_b32_e32 v5, 1.0
	v_mov_b32_e32 v102, 1.0
	v_mov_b32_e32 v103, 1.0
	v_mov_b32_e32 v104, 1.0
	v_mov_b32_e32 v105, 1.0
	v_mov_b32_e32 v106, 1.0
	v_mov_b32_e32 v107, 1.0
	v_mov_b32_e32 v108, 1.0
	v_mov_b32_e32 v109, 1.0
	s_and_saveexec_b64 s[16:17], vcc
	s_cbranch_execz .LBB0_111
	global_load_dwordx4 v[102:105], v[22:23], off
	global_load_dwordx4 v[106:109], v[22:23], off offset:16

; #define LAS __attribute__((address_space(3)))
; template <bool MAPIN>
; __device__ __forceinline__ void transpose_item(const float* W, int K, int N, bf16_t* WT, LAS float* scr, int item, int lane, const float* gk = nullptr) {
;     ...
;     for (int i = 0; i < 32; ++i) { const int kk = 2 * i + (lane >> 5); scr[kk * 33 + (lane & 31)] = W[(size_t)(k0 + kk) * N + n0 + (lane & 31)]; }
;     asm volatile("s_waitcnt lgkmcnt(0)" ::: "memory");
;     const int c = lane & 7;
; #pragma unroll
;     for (int j = 0; j < 4; ++j) { const int n = (lane >> 3) + 8 * j; const LAS float* s = scr + (8 * c) * 33 + n;
;         f32x4 ga = (f32x4){1.f, 1.f, 1.f, 1.f}, gb = ga;
;         if (gk) { ga = *(const f32x4*)(gk + k0 + 8 * c); gb = *(const f32x4*)(gk + k0 + 8 * c + 4); }
.LBB0_120:
	s_lshl_b32 s19, s0, 1
	s_lshl_b32 s20, s1, 1
	v_or_b32_e32 v2, s19, v13
	v_or_b32_e32 v11, s20, v12
	s_add_i32 s21, s19, 4
	s_add_i32 s22, s20, 4
	s_add_i32 s23, s19, 8
	s_add_i32 s24, s20, 8
	s_add_i32 s25, s19, 12
	s_add_i32 s26, s20, 12
	s_add_i32 s27, s19, 16
	s_add_i32 s28, s20, 16
	s_add_i32 s29, s19, 20
	s_add_i32 s30, s20, 20
	s_add_i32 s31, s19, 24
	s_add_i32 s34, s20, 24
	s_add_i32 s19, s19, 28
	s_add_i32 s20, s20, 28
	v_add_u32_e32 v4, v11, v24
	v_or_b32_e32 v14, s21, v13
	v_or_b32_e32 v21, s22, v12
	v_or_b32_e32 v25, s23, v13
	v_or_b32_e32 v62, s24, v12
	v_or_b32_e32 v63, s25, v13
	v_or_b32_e32 v65, s26, v12
	v_or_b32_e32 v67, s27, v13
	v_or_b32_e32 v68, s28, v12
	v_or_b32_e32 v69, s29, v13
	v_or_b32_e32 v70, s30, v12
	v_or_b32_e32 v71, s31, v13
	v_or_b32_e32 v72, s34, v12
	v_or_b32_e32 v73, s19, v13
	v_or_b32_e32 v74, s20, v12
	v_add_u32_e32 v5, v2, v3
	v_mul_lo_u32 v4, v4, s46
	v_add_u32_e32 v9, v14, v3
	v_add_u32_e32 v8, v21, v24
	v_add_u32_e32 v23, v25, v3
	v_add_u32_e32 v38, v62, v24
	v_add_u32_e32 v39, v63, v3
	v_add_u32_e32 v41, v65, v24
	v_add_u32_e32 v43, v67, v3
	v_add_u32_e32 v45, v68, v24
	v_add_u32_e32 v47, v69, v3
	v_add_u32_e32 v49, v70, v24
	v_add_u32_e32 v51, v71, v3
	v_add_u32_e32 v53, v72, v24
	v_add_u32_e32 v55, v73, v3
	v_add_u32_e32 v57, v74, v24
	v_mul_lo_u32 v6, v5, s46
	v_ashrrev_i32_e32 v5, 31, v4
	v_mul_lo_u32 v8, v8, s46
	v_mul_lo_u32 v22, v9, s46
	v_mul_lo_u32 v38, v38, s46
	v_mul_lo_u32 v40, v23, s46
	v_mul_lo_u32 v42, v41, s46
	v_mul_lo_u32 v44, v39, s46
	v_mul_lo_u32 v46, v45, s46
	v_mul_lo_u32 v48, v43, s46
	v_mul_lo_u32 v50, v49, s46
	v_mul_lo_u32 v52, v47, s46
	v_mul_lo_u32 v54, v53, s46
	v_mul_lo_u32 v56, v51, s46
	v_mul_lo_u32 v58, v57, s46
	v_mul_lo_u32 v60, v55, s46
	v_ashrrev_i32_e32 v7, 31, v6
	v_lshl_add_u64 v[4:5], v[0:1], 0, v[4:5]
	v_ashrrev_i32_e32 v23, 31, v22
	v_ashrrev_i32_e32 v9, 31, v8
	v_ashrrev_i32_e32 v41, 31, v40
	v_ashrrev_i32_e32 v39, 31, v38
	v_ashrrev_i32_e32 v45, 31, v44
	v_ashrrev_i32_e32 v43, 31, v42
	v_ashrrev_i32_e32 v49, 31, v48
	v_ashrrev_i32_e32 v47, 31, v46
	v_ashrrev_i32_e32 v53, 31, v52
	v_ashrrev_i32_e32 v51, 31, v50
	v_ashrrev_i32_e32 v57, 31, v56
	v_ashrrev_i32_e32 v55, 31, v54
	v_ashrrev_i32_e32 v61, 31, v60
	v_ashrrev_i32_e32 v59, 31, v58
	v_lshl_add_u64 v[6:7], v[0:1], 0, v[6:7]
	v_lshl_add_u64 v[8:9], v[0:1], 0, v[8:9]
	v_lshl_add_u64 v[22:23], v[0:1], 0, v[22:23]
	v_lshl_add_u64 v[38:39], v[0:1], 0, v[38:39]
	v_lshl_add_u64 v[40:41], v[0:1], 0, v[40:41]
	v_lshl_add_u64 v[42:43], v[0:1], 0, v[42:43]
	v_lshl_add_u64 v[44:45], v[0:1], 0, v[44:45]
	v_lshl_add_u64 v[46:47], v[0:1], 0, v[46:47]
	v_lshl_add_u64 v[48:49], v[0:1], 0, v[48:49]
	v_lshl_add_u64 v[50:51], v[0:1], 0, v[50:51]
	v_lshl_add_u64 v[52:53], v[0:1], 0, v[52:53]
	v_lshl_add_u64 v[54:55], v[0:1], 0, v[54:55]
	v_lshl_add_u64 v[56:57], v[0:1], 0, v[56:57]
	v_lshl_add_u64 v[58:59], v[0:1], 0, v[58:59]
	v_lshl_add_u64 v[60:61], v[0:1], 0, v[60:61]
	global_load_dword v75, v[4:5], off nt
	global_load_dword v76, v[6:7], off nt
	global_load_dword v77, v[8:9], off nt
	global_load_dword v78, v[22:23], off nt
	global_load_dword v79, v[38:39], off nt
	global_load_dword v80, v[40:41], off nt
	global_load_dword v81, v[42:43], off nt
	global_load_dword v82, v[44:45], off nt
	global_load_dword v83, v[46:47], off nt
	global_load_dword v84, v[48:49], off nt
	global_load_dword v85, v[50:51], off nt
	global_load_dword v86, v[52:53], off nt
	global_load_dword v87, v[54:55], off nt
	global_load_dword v88, v[56:57], off nt
	global_load_dword v89, v[58:59], off nt
	global_load_dword v90, v[60:61], off nt
	s_add_i32 s1, s1, 16
	s_add_i32 s0, s0, 16
	s_add_i32 s18, s18, -16
	v_mad_u64_u32 v[4:5], s[20:21], v11, s36, v[16:17]
	s_cmp_lg_u32 s18, 0
	v_mad_u64_u32 v[6:7], s[20:21], v2, s36, v[16:17]
	v_mad_u64_u32 v[8:9], s[20:21], v21, s36, v[16:17]
	v_mad_u64_u32 v[22:23], s[20:21], v14, s36, v[16:17]
	v_mad_u64_u32 v[38:39], s[20:21], v62, s36, v[16:17]
	v_mad_u64_u32 v[40:41], s[20:21], v25, s36, v[16:17]
	v_mad_u64_u32 v[42:43], s[20:21], v65, s36, v[16:17]
	v_mad_u64_u32 v[44:45], s[20:21], v63, s36, v[16:17]
	v_mad_u64_u32 v[46:47], s[20:21], v68, s36, v[16:17]
	v_mad_u64_u32 v[48:49], s[20:21], v67, s36, v[16:17]
	v_mad_u64_u32 v[50:51], s[20:21], v70, s36, v[16:17]
	v_mad_u64_u32 v[52:53], s[20:21], v69, s36, v[16:17]
	v_mad_u64_u32 v[54:55], s[20:21], v72, s36, v[16:17]
	v_mad_u64_u32 v[56:57], s[20:21], v71, s36, v[16:17]
	v_mad_u64_u32 v[58:59], s[20:21], v74, s36, v[16:17]
	v_mad_u64_u32 v[60:61], s[20:21], v73, s36, v[16:17]
	s_lshl_b32 s19, s0, 1
	s_lshl_b32 s20, s1, 1
	v_or_b32_e32 v132, s19, v13
	v_or_b32_e32 v141, s20, v12
	s_add_i32 s21, s19, 4
	s_add_i32 s22, s20, 4
	s_add_i32 s23, s19, 8
	s_add_i32 s24, s20, 8
	s_add_i32 s25, s19, 12
	s_add_i32 s26, s20, 12
	s_add_i32 s27, s19, 16
	s_add_i32 s28, s20, 16
	s_add_i32 s29, s19, 20
	s_add_i32 s30, s20, 20
	s_add_i32 s31, s19, 24
	s_add_i32 s34, s20, 24
	s_add_i32 s19, s19, 28
	s_add_i32 s20, s20, 28
	v_add_u32_e32 v134, v141, v24
	v_or_b32_e32 v144, s21, v13
	v_or_b32_e32 v151, s22, v12
	v_or_b32_e32 v155, s23, v13
	v_or_b32_e32 v192, s24, v12
	v_or_b32_e32 v193, s25, v13
	v_or_b32_e32 v195, s26, v12
	v_or_b32_e32 v197, s27, v13
	v_or_b32_e32 v198, s28, v12
	v_or_b32_e32 v199, s29, v13
	v_or_b32_e32 v200, s30, v12
	v_or_b32_e32 v201, s31, v13
	v_or_b32_e32 v202, s34, v12
	v_or_b32_e32 v203, s19, v13
	v_or_b32_e32 v204, s20, v12
	v_add_u32_e32 v135, v132, v3
	v_mul_lo_u32 v134, v134, s46
	v_add_u32_e32 v139, v144, v3
	v_add_u32_e32 v138, v151, v24
	v_add_u32_e32 v153, v155, v3
; #define LAS __attribute__((address_space(3)))
; template <bool MAPIN>
; __device__ __forceinline__ void transpose_item(const float* W, int K, int N, bf16_t* WT, LAS float* scr, int item, int lane, const float* gk = nullptr) {
;     ...
;     for (int i = 0; i < 32; ++i) { const int kk = 2 * i + (lane >> 5); scr[kk * 33 + (lane & 31)] = W[(size_t)(k0 + kk) * N + n0 + (lane & 31)]; }
;     asm volatile("s_waitcnt lgkmcnt(0)" ::: "memory");
;     const int c = lane & 7;
; #pragma unroll
;     for (int j = 0; j < 4; ++j) { const int n = (lane >> 3) + 8 * j; const LAS float* s = scr + (8 * c) * 33 + n;
;         f32x4 ga = (f32x4){1.f, 1.f, 1.f, 1.f}, gb = ga;
;         if (gk) { ga = *(const f32x4*)(gk + k0 + 8 * c); gb = *(const f32x4*)(gk + k0 + 8 * c + 4); }
	v_add_u32_e32 v168, v192, v24
	v_add_u32_e32 v169, v193, v3
	v_add_u32_e32 v171, v195, v24
	v_add_u32_e32 v173, v197, v3
	v_add_u32_e32 v175, v198, v24
	v_add_u32_e32 v177, v199, v3
	v_add_u32_e32 v179, v200, v24
	v_add_u32_e32 v181, v201, v3
	v_add_u32_e32 v183, v202, v24
	v_add_u32_e32 v185, v203, v3
	v_add_u32_e32 v187, v204, v24
	v_mul_lo_u32 v136, v135, s46
	v_ashrrev_i32_e32 v135, 31, v134
	v_mul_lo_u32 v138, v138, s46
	v_mul_lo_u32 v152, v139, s46
	v_mul_lo_u32 v168, v168, s46
	v_mul_lo_u32 v170, v153, s46
	v_mul_lo_u32 v172, v171, s46
	v_mul_lo_u32 v174, v169, s46
	v_mul_lo_u32 v176, v175, s46
	v_mul_lo_u32 v178, v173, s46
	v_mul_lo_u32 v180, v179, s46
	v_mul_lo_u32 v182, v177, s46
	v_mul_lo_u32 v184, v183, s46
	v_mul_lo_u32 v186, v181, s46
	v_mul_lo_u32 v188, v187, s46
	v_mul_lo_u32 v190, v185, s46
	v_ashrrev_i32_e32 v137, 31, v136
	v_lshl_add_u64 v[134:135], v[0:1], 0, v[134:135]
	v_ashrrev_i32_e32 v153, 31, v152
	v_ashrrev_i32_e32 v139, 31, v138
	v_ashrrev_i32_e32 v171, 31, v170
	v_ashrrev_i32_e32 v169, 31, v168
	v_ashrrev_i32_e32 v175, 31, v174
	v_ashrrev_i32_e32 v173, 31, v172
	v_ashrrev_i32_e32 v179, 31, v178
	v_ashrrev_i32_e32 v177, 31, v176
	v_ashrrev_i32_e32 v183, 31, v182
	v_ashrrev_i32_e32 v181, 31, v180
	v_ashrrev_i32_e32 v187, 31, v186
	v_ashrrev_i32_e32 v185, 31, v184
	v_ashrrev_i32_e32 v191, 31, v190
	v_ashrrev_i32_e32 v189, 31, v188
	v_lshl_add_u64 v[136:137], v[0:1], 0, v[136:137]
	v_lshl_add_u64 v[138:139], v[0:1], 0, v[138:139]
	v_lshl_add_u64 v[152:153], v[0:1], 0, v[152:153]
	v_lshl_add_u64 v[168:169], v[0:1], 0, v[168:169]
	v_lshl_add_u64 v[170:171], v[0:1], 0, v[170:171]
	v_lshl_add_u64 v[172:173], v[0:1], 0, v[172:173]
	v_lshl_add_u64 v[174:175], v[0:1], 0, v[174:175]
	v_lshl_add_u64 v[176:177], v[0:1], 0, v[176:177]
	v_lshl_add_u64 v[178:179], v[0:1], 0, v[178:179]
	v_lshl_add_u64 v[180:181], v[0:1], 0, v[180:181]
	v_lshl_add_u64 v[182:183], v[0:1], 0, v[182:183]
	v_lshl_add_u64 v[184:185], v[0:1], 0, v[184:185]
	v_lshl_add_u64 v[186:187], v[0:1], 0, v[186:187]
	v_lshl_add_u64 v[188:189], v[0:1], 0, v[188:189]
	v_lshl_add_u64 v[190:191], v[0:1], 0, v[190:191]
	global_load_dword v205, v[134:135], off nt
	global_load_dword v206, v[136:137], off nt
	global_load_dword v207, v[138:139], off nt
	global_load_dword v208, v[152:153], off nt
	global_load_dword v209, v[168:169], off nt
	global_load_dword v210, v[170:171], off nt
	global_load_dword v211, v[172:173], off nt
	global_load_dword v212, v[174:175], off nt
	global_load_dword v213, v[176:177], off nt
	global_load_dword v214, v[178:179], off nt
	global_load_dword v215, v[180:181], off nt
	global_load_dword v216, v[182:183], off nt
	global_load_dword v217, v[184:185], off nt
	global_load_dword v218, v[186:187], off nt
	global_load_dword v219, v[188:189], off nt
	global_load_dword v220, v[190:191], off nt
	s_add_i32 s1, s1, 16
	s_add_i32 s0, s0, 16
	s_add_i32 s18, s18, -16
	v_mad_u64_u32 v[134:135], s[20:21], v141, s36, v[16:17]
	s_cmp_lg_u32 s18, 0
	v_mad_u64_u32 v[136:137], s[20:21], v132, s36, v[16:17]
	v_mad_u64_u32 v[138:139], s[20:21], v151, s36, v[16:17]
	v_mad_u64_u32 v[152:153], s[20:21], v144, s36, v[16:17]
	v_mad_u64_u32 v[168:169], s[20:21], v192, s36, v[16:17]
	v_mad_u64_u32 v[170:171], s[20:21], v155, s36, v[16:17]
	v_mad_u64_u32 v[172:173], s[20:21], v195, s36, v[16:17]
	v_mad_u64_u32 v[174:175], s[20:21], v193, s36, v[16:17]
	v_mad_u64_u32 v[176:177], s[20:21], v198, s36, v[16:17]
	v_mad_u64_u32 v[178:179], s[20:21], v197, s36, v[16:17]
	v_mad_u64_u32 v[180:181], s[20:21], v200, s36, v[16:17]
	v_mad_u64_u32 v[182:183], s[20:21], v199, s36, v[16:17]
	v_mad_u64_u32 v[184:185], s[20:21], v202, s36, v[16:17]
	v_mad_u64_u32 v[186:187], s[20:21], v201, s36, v[16:17]
	v_mad_u64_u32 v[188:189], s[20:21], v204, s36, v[16:17]
	v_mad_u64_u32 v[190:191], s[20:21], v203, s36, v[16:17]
	s_waitcnt vmcnt(0)
	ds_write_b32 v4, v75
	ds_write_b32 v6, v76
	ds_write_b32 v8, v77
	ds_write_b32 v22, v78
	ds_write_b32 v38, v79
	ds_write_b32 v40, v80
	ds_write_b32 v42, v81
	ds_write_b32 v44, v82
	ds_write_b32 v46, v83
	ds_write_b32 v48, v84
	ds_write_b32 v50, v85
	ds_write_b32 v52, v86
	ds_write_b32 v54, v87
	ds_write_b32 v56, v88
	ds_write_b32 v58, v89
	ds_write_b32 v60, v90
	ds_write_b32 v134, v205
	ds_write_b32 v136, v206
	ds_write_b32 v138, v207
	ds_write_b32 v152, v208
	ds_write_b32 v168, v209
	ds_write_b32 v170, v210
	ds_write_b32 v172, v211
	ds_write_b32 v174, v212
	ds_write_b32 v176, v213
	ds_write_b32 v178, v214
	ds_write_b32 v180, v215
	ds_write_b32 v182, v216
	ds_write_b32 v184, v217
	ds_write_b32 v186, v218
	ds_write_b32 v188, v219
	ds_write_b32 v190, v220
	v_add_u32_e32 v0, 0xffffc400, v36
	v_cmp_lt_u32_e32 vcc, s47, v0
	v_mov_b32_e32 v1, s40
	v_cmp_gt_u32_e64 s[0:1], s48, v0
	v_mov_b32_e32 v0, s39
	s_waitcnt lgkmcnt(0)
	v_ashrrev_i32_e32 v25, 31, v24
	v_cndmask_b32_e64 v1, v1, 0, s[0:1]
	v_cndmask_b32_e64 v0, v0, 0, s[0:1]
	v_lshl_add_u64 v[0:1], v[24:25], 2, v[0:1]
	v_lshlrev_b32_e32 v14, 2, v18
	v_lshl_add_u64 v[22:23], v[0:1], 0, v[14:15]
	v_mov_b32_e32 v6, 1.0
	v_mov_b32_e32 v7, 1.0
	v_mov_b32_e32 v8, 1.0
	v_mov_b32_e32 v9, 1.0
	v_mov_b32_e32 v2, 1.0
	v_mov_b32_e32 v3, 1.0
	v_mov_b32_e32 v4, 1.0
	v_mov_b32_e32 v5, 1.0
	v_mov_b32_e32 v102, 1.0
	v_mov_b32_e32 v103, 1.0
	v_mov_b32_e32 v104, 1.0
	v_mov_b32_e32 v105, 1.0
	v_mov_b32_e32 v106, 1.0
	v_mov_b32_e32 v107, 1.0
	v_mov_b32_e32 v108, 1.0
	v_mov_b32_e32 v109, 1.0
	s_and_saveexec_b64 s[0:1], vcc
	s_cbranch_execz .LBB0_123
	global_load_dwordx4 v[102:105], v[22:23], off
	global_load_dwordx4 v[106:109], v[22:23], off offset:16
